# v63 + FFN2 down-weight conversion (conv segment 12) moved from P5 into the idle tail of the 64 workgroups that finish the dilated phase early
# speedup vs baseline: 1.0039x; 1.0039x over previous
.LBB0_613:
	v_readlane_b32 s70, v248, 0
	v_readlane_b32 s71, v248, 1
	s_cmpk_lg_i32 s79, 0x100
	s_cbranch_scc1 .Lp4c_skip
	s_cmpk_gt_i32 s82, 63
	s_cbranch_scc1 .Lp4c_skip
	s_mov_b32 s100, s12
	s_mov_b32 s101, s14
	s_lshl_b32 s12, s82, 3
	s_add_i32 s12, s12, s83
	s_movk_i32 s14, 0x200
	s_mov_b64 s[0:1], s[70:71]
	s_load_dwordx2 s[4:5], s[0:1], 0xb8
	s_lshl_b32 s0, s83, 14
	s_mov_b64 s[6:7], s[70:71]
	s_add_i32 s2, s0, 0
	s_waitcnt lgkmcnt(0)
	v_mbcnt_hi_u32_b32 v168, -1, v187
	s_add_u32 s8, s6, 0x98
	s_addc_u32 s9, s7, 0
	v_lshlrev_b32_e32 v3, 3, v168
	s_add_u32 s16, s6, 0xa8
	v_lshrrev_b32_e32 v42, 3, v168
	v_and_b32_e32 v3, 56, v3
	s_addc_u32 s17, s7, 0
	v_and_b32_e32 v144, 64, v168
	v_mul_u32_u24_e32 v4, 0x84, v3
	v_lshlrev_b32_e32 v32, 2, v42
	s_abs_i32 s15, s14
	v_add_u32_e32 v44, 8, v42
	v_or_b32_e32 v1, v42, v144
	v_add3_u32 v47, s2, v4, v32
	v_cvt_f32_u32_e32 v4, s15
	v_or_b32_e32 v45, 16, v42
	v_lshlrev_b32_e32 v48, 2, v1
	v_or_b32_e32 v1, v44, v144
	v_add_u32_e32 v46, 24, v42
	v_lshlrev_b32_e32 v49, 2, v1
	v_or_b32_e32 v1, v45, v144
	v_lshlrev_b32_e32 v50, 2, v1
	v_or_b32_e32 v1, v46, v144
	v_lshlrev_b32_e32 v51, 2, v1
	v_rcp_iflag_f32_e32 v1, v4
	s_load_dwordx2 s[0:1], s[6:7], 0xb8
	v_mov_b32_e32 v35, 0
	v_lshlrev_b32_e32 v34, 1, v3
	v_mul_f32_e32 v1, 0x4f7ffffe, v1
	v_cvt_u32_f32_e32 v1, v1
	s_waitcnt lgkmcnt(0)
	v_lshl_add_u64 v[36:37], s[0:1], 0, v[34:35]
	s_sub_i32 s0, 0, s15
	v_lshlrev_b32_e32 v0, 2, v168
	v_readfirstlane_b32 s1, v1
	v_add_u32_e32 v2, 56, v42
	s_mul_i32 s0, s0, s1
	v_and_b32_e32 v0, 28, v0
	v_and_or_b32 v2, v2, 63, v144
	s_mul_hi_u32 s0, s1, s0
	s_mov_b32 s13, 0
	v_lshl_add_u32 v33, v0, 2, s2
	v_mul_u32_u24_e32 v43, 0x84, v42
	v_or_b32_e32 v52, 0x80, v48
	v_add_u32_e32 v53, 0xa0, v48
	v_or_b32_e32 v54, 0xc0, v48
	v_lshlrev_b32_e32 v55, 2, v2
	s_add_i32 s33, s1, s0
	s_mov_b32 s34, 0x8000
	s_mov_b64 s[0:1], 0
	s_mov_b64 s[18:19], -1
	v_lshlrev_b32_e32 v34, 2, v0
	s_branch .Lp4c_662

.Lp4c_done:
	s_waitcnt vmcnt(0) lgkmcnt(0)
	s_barrier
	s_mov_b32 s12, s100
	s_mov_b32 s14, s101
.Lp4c_skip:
.LBB0_614:
	s_cmp_gt_i32 s87, 5
	s_cselect_b64 s[0:1], -1, 0
	s_and_b64 s[2:3], s[10:11], s[0:1]
	s_andn2_b64 vcc, exec, s[2:3]
	s_cbranch_vccnz .LBB0_659
	s_waitcnt vmcnt(0)
	s_waitcnt vmcnt(0) lgkmcnt(0)
	s_barrier
	s_and_saveexec_b64 s[2:3], s[90:91]
	s_cbranch_execz .LBB0_658
	s_add_i32 s4, 0, 0x23fc0
	v_mov_b32_e32 v0, s4
	s_waitcnt vmcnt(0) expcnt(0) lgkmcnt(0)
	ds_read_b32 v2, v0
	s_add_i32 s4, 0, 0x23fc4
	v_mov_b32_e32 v0, s4
	ds_read_b32 v0, v0
	s_waitcnt lgkmcnt(1)
	v_cmp_ne_u32_e32 vcc, 0, v2
	s_cbranch_vccnz .LBB0_629
	s_load_dwordx2 s[8:9], s[88:89], 0x4
	s_add_u32 s4, s84, 0x1000
	s_addc_u32 s5, s85, 0
	s_add_u32 s6, s84, 0x1100
	s_addc_u32 s7, s85, 0
	s_waitcnt lgkmcnt(0)
	s_mul_i32 s13, s8, s79
	s_add_u32 s8, s84, 0x1200
	s_mul_i32 s13, s13, s9
	s_addc_u32 s9, s85, 0
	s_add_u32 s10, s84, 0x1300
	s_addc_u32 s11, s85, 0
	s_mov_b32 s15, 1
	v_mov_b32_e32 v16, 0
	s_branch .LBB0_619

.LBB0_659:
	s_cmp_lt_i32 s81, 6
	s_cselect_b64 s[2:3], -1, 0
	s_and_b64 s[10:11], s[2:3], s[0:1]
	s_andn2_b64 vcc, exec, s[10:11]
	s_cbranch_vccnz .LBB0_831
	s_mov_b64 s[0:1], s[70:71]
	s_load_dwordx2 s[4:5], s[0:1], 0xb8
	s_lshl_b32 s0, s83, 14
	s_mov_b64 s[6:7], s[70:71]
	s_add_i32 s2, s0, 0
	s_waitcnt lgkmcnt(0)
	v_mbcnt_hi_u32_b32 v168, -1, v187
	s_add_u32 s8, s6, 0x98
	s_addc_u32 s9, s7, 0
	v_lshlrev_b32_e32 v3, 3, v168
	s_add_u32 s16, s6, 0xa8
	v_lshrrev_b32_e32 v42, 3, v168
	v_and_b32_e32 v3, 56, v3
	s_addc_u32 s17, s7, 0
	v_and_b32_e32 v144, 64, v168
	v_mul_u32_u24_e32 v4, 0x84, v3
	v_lshlrev_b32_e32 v32, 2, v42
	s_abs_i32 s15, s14
	v_add_u32_e32 v44, 8, v42
	v_or_b32_e32 v1, v42, v144
	v_add3_u32 v47, s2, v4, v32
	v_cvt_f32_u32_e32 v4, s15
	v_or_b32_e32 v45, 16, v42
	v_lshlrev_b32_e32 v48, 2, v1
	v_or_b32_e32 v1, v44, v144
	v_add_u32_e32 v46, 24, v42
	v_lshlrev_b32_e32 v49, 2, v1
	v_or_b32_e32 v1, v45, v144
	v_lshlrev_b32_e32 v50, 2, v1
	v_or_b32_e32 v1, v46, v144
	v_lshlrev_b32_e32 v51, 2, v1
	v_rcp_iflag_f32_e32 v1, v4
	s_load_dwordx2 s[0:1], s[6:7], 0xb8
	v_mov_b32_e32 v35, 0
	v_lshlrev_b32_e32 v34, 1, v3
	v_mul_f32_e32 v1, 0x4f7ffffe, v1
	v_cvt_u32_f32_e32 v1, v1
	s_waitcnt lgkmcnt(0)
	v_lshl_add_u64 v[36:37], s[0:1], 0, v[34:35]
	s_sub_i32 s0, 0, s15
	v_lshlrev_b32_e32 v0, 2, v168
	v_readfirstlane_b32 s1, v1
	v_add_u32_e32 v2, 56, v42
	s_mul_i32 s0, s0, s1
	v_and_b32_e32 v0, 28, v0
	v_and_or_b32 v2, v2, 63, v144
	s_mul_hi_u32 s0, s1, s0
	s_mov_b32 s13, 0
	v_lshl_add_u32 v33, v0, 2, s2
	v_mul_u32_u24_e32 v43, 0x84, v42
	v_or_b32_e32 v52, 0x80, v48
	v_add_u32_e32 v53, 0xa0, v48
	v_or_b32_e32 v54, 0xc0, v48
	v_lshlrev_b32_e32 v55, 2, v2
	s_add_i32 s33, s1, s0
	s_lshl_b32 s34, s79, 9
	s_mov_b64 s[0:1], -1
	s_mov_b64 s[18:19], 0
	s_cmpk_eq_i32 s79, 0x100
	s_cselect_b64 s[18:19], -1, 0
	v_lshlrev_b32_e32 v34, 2, v0
	s_branch .LBB0_662
